# v56 plus lever 2 in the FF1 phase: each tile's four bias reads requested at the top of the tile (spare v226..v241) and copied in the epilogue instead of read + vmcnt(0) there
# speedup vs baseline: 1.0139x; 1.0139x over previous
.LBB0_578:
	v_lshl_or_b32 v226, s77, 8, v167
	v_ashrrev_i32_e32 v227, 31, v226
	v_lshl_add_u64 v[226:227], v[226:227], 2, s[42:43]
	global_load_dwordx4 v[230:233], v[226:227], off offset:16
	global_load_dwordx4 v[234:237], v[226:227], off offset:512
	global_load_dwordx4 v[238:241], v[226:227], off offset:528
	global_load_dwordx4 v[226:229], v[226:227], off
	s_add_i32 s63, s63, 1
	s_mul_i32 s4, s63, s70
	s_mul_hi_u32 s5, s63, s33
	s_add_i32 s5, s5, s4
	s_mul_i32 s4, s63, s33
	s_add_u32 s4, s4, s38
	s_addc_u32 s5, s5, s0
	v_cmp_gt_i64_e32 vcc, s[4:5], v[160:161]
	v_cmp_lt_i64_e64 s[6:7], s[4:5], v[158:159]
	s_cbranch_vccnz .LBB0_580
	s_ashr_i32 s5, s4, 31
	s_lshr_b32 s5, s5, 29
	s_add_i32 s5, s4, s5
	s_ashr_i32 s28, s5, 3
	s_and_b32 s5, s5, -8
	s_sub_i32 s4, s4, s5
	s_cmp_lt_i32 s4, 0
	s_cselect_b32 s5, s1, 0x60
	s_mul_i32 s4, s4, s5
	s_add_i32 s4, s4, s28
	s_mul_hi_i32 s5, s4, 0x2aaaaaab
	s_lshr_b32 s28, s5, 31
	s_ashr_i32 s5, s5, 4
	s_add_i32 s5, s5, s28
	s_mul_i32 s29, s5, 6
	s_sub_i32 s28, 48, s29
	s_min_i32 s30, s28, 6
	s_abs_i32 s28, s30
	v_cvt_f32_u32_e32 v2, s28
	s_sub_i32 s34, 0, s28
	s_mulk_i32 s5, 0x60
	s_sub_i32 s4, s4, s5
	v_rcp_iflag_f32_e32 v2, v2
	s_abs_i32 s5, s4
	s_xor_b32 s31, s4, s30
	s_ashr_i32 s31, s31, 31
	v_mul_f32_e32 v2, 0x4f7ffffe, v2
	v_cvt_u32_f32_e32 v2, v2
	s_nop 0
	v_readfirstlane_b32 s35, v2
	s_mul_i32 s34, s34, s35
	s_mul_hi_u32 s34, s35, s34
	s_add_i32 s35, s35, s34
	s_mul_hi_u32 s34, s5, s35
	s_mul_i32 s35, s34, s28
	s_sub_i32 s5, s5, s35
	s_add_i32 s36, s34, 1
	s_sub_i32 s35, s5, s28
	s_cmp_ge_u32 s5, s28
	s_cselect_b32 s34, s36, s34
	s_cselect_b32 s5, s35, s5
	s_add_i32 s35, s34, 1
	s_cmp_ge_u32 s5, s28
	s_cselect_b32 s5, s35, s34
	s_xor_b32 s5, s5, s31
	s_sub_i32 s28, s5, s31
	s_mul_i32 s5, s28, s30
	s_sub_i32 s4, s4, s5
	s_add_i32 s30, s29, s4

.LBB0_584:
	v_lshl_or_b32 v162, s77, 8, v167
	v_ashrrev_i32_e32 v163, 31, v162
	v_lshl_add_u64 v[130:131], v[162:163], 2, s[42:43]
	v_lshl_add_u32 v164, s40, 8, v1
	v_ashrrev_i32_e32 v165, 31, v164
	v_or_b32_e32 v172, 16, v164
	v_lshlrev_b64 v[174:175], 13, v[164:165]
	v_lshlrev_b64 v[176:177], 1, v[162:163]
	v_ashrrev_i32_e32 v173, 31, v172
	v_lshl_add_u64 v[162:163], s[68:69], 0, v[174:175]
	v_lshlrev_b64 v[172:173], 13, v[172:173]
	v_lshl_add_u64 v[162:163], v[162:163], 0, v[176:177]
	v_lshl_add_u64 v[172:173], s[68:69], 0, v[172:173]
	v_lshl_add_u64 v[172:173], v[172:173], 0, v[176:177]
	s_mov_b64 s[4:5], -1
	s_waitcnt vmcnt(0)
	v_mov_b32_e32 v142, v226
	v_mov_b32_e32 v143, v227
	v_mov_b32_e32 v144, v228
	v_mov_b32_e32 v145, v229
	v_mov_b32_e32 v138, v230
	v_mov_b32_e32 v139, v231
	v_mov_b32_e32 v140, v232
	v_mov_b32_e32 v141, v233
	v_mov_b32_e32 v134, v234
	v_mov_b32_e32 v135, v235
	v_mov_b32_e32 v136, v236
	v_mov_b32_e32 v137, v237
	v_mov_b32_e32 v130, v238
	v_mov_b32_e32 v131, v239
	v_mov_b32_e32 v132, v240
	v_mov_b32_e32 v133, v241
	v_pk_add_f32 v[126:127], v[126:127], v[142:143]
	v_pk_add_f32 v[128:129], v[128:129], v[144:145]
	v_pk_add_f32 v[124:125], v[124:125], v[140:141]
	v_pk_add_f32 v[106:107], v[106:107], v[130:131]
	v_pk_add_f32 v[122:123], v[122:123], v[138:139]
	v_pk_add_f32 v[110:111], v[110:111], v[134:135]
	v_pk_add_f32 v[108:109], v[108:109], v[132:133]
	v_max_f32_e32 v126, 0, v126
	v_max_f32_e32 v127, 0, v127
	v_max_f32_e32 v106, 0, v106
	v_pk_add_f32 v[112:113], v[112:113], v[136:137]
	v_pk_add_f32 v[118:119], v[118:119], v[142:143]
	v_max_f32_e32 v122, 0, v122
	v_max_f32_e32 v123, 0, v123
	v_max_f32_e32 v128, 0, v128
	v_max_f32_e32 v124, 0, v124
	v_max_f32_e32 v129, 0, v129
	v_max_f32_e32 v125, 0, v125
	v_max_f32_e32 v110, 0, v110
	v_max_f32_e32 v111, 0, v111
	v_max_f32_e32 v107, 0, v107
	v_max_f32_e32 v108, 0, v108
	v_max_f32_e32 v109, 0, v109
	v_mul_f32_e32 v126, v126, v126
	v_mul_f32_e32 v127, v127, v127
	v_mul_f32_e32 v165, v106, v106
	v_cvt_pk_bf16_f32 v106, v126, v127
	v_pk_add_f32 v[120:121], v[120:121], v[144:145]
	v_pk_add_f32 v[116:117], v[116:117], v[140:141]
	v_pk_add_f32 v[114:115], v[114:115], v[138:139]
	v_max_f32_e32 v112, 0, v112
	v_max_f32_e32 v113, 0, v113
	v_max_f32_e32 v118, 0, v118
	v_max_f32_e32 v119, 0, v119
	v_mul_f32_e32 v122, v122, v122
	v_mul_f32_e32 v123, v123, v123
	v_mul_f32_e32 v128, v128, v128
	v_mul_f32_e32 v124, v124, v124
	v_mul_f32_e32 v129, v129, v129
	v_mul_f32_e32 v125, v125, v125
	v_mul_f32_e32 v110, v110, v110
	v_mul_f32_e32 v111, v111, v111
	v_mul_f32_e32 v171, v107, v107
	v_mul_f32_e32 v174, v108, v108
	v_mul_f32_e32 v175, v109, v109
	v_cvt_pk_bf16_f32 v107, v128, v129
	v_cvt_pk_bf16_f32 v108, v122, v123
	v_cvt_pk_bf16_f32 v109, v124, v125
	global_store_dwordx4 v[162:163], v[106:109], off
	v_pk_add_f32 v[98:99], v[98:99], v[130:131]
	v_max_f32_e32 v114, 0, v114
	v_cvt_pk_bf16_f32 v106, v110, v111
	v_max_f32_e32 v115, 0, v115
	v_max_f32_e32 v120, 0, v120
	v_max_f32_e32 v116, 0, v116
	v_max_f32_e32 v121, 0, v121
	v_max_f32_e32 v117, 0, v117
	v_mul_f32_e32 v112, v112, v112
	v_mul_f32_e32 v113, v113, v113
	v_mul_f32_e32 v118, v118, v118
	v_mul_f32_e32 v119, v119, v119
	v_cvt_pk_bf16_f32 v107, v112, v113
	v_cvt_pk_bf16_f32 v108, v165, v171
	v_cvt_pk_bf16_f32 v109, v174, v175
	global_store_dwordx4 v[162:163], v[106:109], off offset:256
	v_pk_add_f32 v[102:103], v[102:103], v[134:135]
	v_pk_add_f32 v[100:101], v[100:101], v[132:133]
	v_cvt_pk_bf16_f32 v106, v118, v119
	v_max_f32_e32 v98, 0, v98
	v_mul_f32_e32 v114, v114, v114
	v_mul_f32_e32 v115, v115, v115
	v_mul_f32_e32 v120, v120, v120
	v_mul_f32_e32 v116, v116, v116
	v_mul_f32_e32 v121, v121, v121
	v_mul_f32_e32 v117, v117, v117
	v_cvt_pk_bf16_f32 v107, v120, v121
	v_cvt_pk_bf16_f32 v108, v114, v115
	v_cvt_pk_bf16_f32 v109, v116, v117
	global_store_dwordx4 v[172:173], v[106:109], off
	v_pk_add_f32 v[104:105], v[104:105], v[136:137]
	v_max_f32_e32 v99, 0, v99
	v_mul_f32_e32 v106, v98, v98
	v_max_f32_e32 v98, 0, v103
	v_max_f32_e32 v100, 0, v100
	v_max_f32_e32 v102, 0, v102
	v_mul_f32_e32 v98, v98, v98
	v_mul_f32_e32 v103, v99, v99
	v_max_f32_e32 v99, 0, v104
	v_mul_f32_e32 v104, v100, v100
	v_max_f32_e32 v100, 0, v105
	v_max_f32_e32 v101, 0, v101
	v_mul_f32_e32 v102, v102, v102
	v_mul_f32_e32 v99, v99, v99
	v_mul_f32_e32 v100, v100, v100
	v_mul_f32_e32 v101, v101, v101
	v_cvt_pk_bf16_f32 v98, v102, v98
	v_cvt_pk_bf16_f32 v99, v99, v100
	v_cvt_pk_bf16_f32 v100, v106, v103
	v_cvt_pk_bf16_f32 v101, v104, v101
	global_store_dwordx4 v[172:173], v[98:101], off offset:256
	v_pk_add_f32 v[90:91], v[90:91], v[138:139]
	v_pk_add_f32 v[94:95], v[94:95], v[142:143]
	v_or_b32_e32 v98, 32, v164
	v_ashrrev_i32_e32 v99, 31, v98
	v_pk_add_f32 v[92:93], v[92:93], v[140:141]
	v_max_f32_e32 v90, 0, v90
	v_lshlrev_b64 v[98:99], 13, v[98:99]
	v_pk_add_f32 v[96:97], v[96:97], v[144:145]
	v_mul_f32_e32 v100, v90, v90
	v_max_f32_e32 v90, 0, v95
	v_max_f32_e32 v91, 0, v91
	v_max_f32_e32 v92, 0, v92
	v_lshl_add_u64 v[98:99], s[68:69], 0, v[98:99]
	v_max_f32_e32 v94, 0, v94
	v_mul_f32_e32 v90, v90, v90
	v_mul_f32_e32 v95, v91, v91
	v_max_f32_e32 v91, 0, v96
	v_mul_f32_e32 v96, v92, v92
	v_max_f32_e32 v92, 0, v97
	v_max_f32_e32 v93, 0, v93
	v_pk_add_f32 v[82:83], v[82:83], v[130:131]
	v_lshl_add_u64 v[98:99], v[98:99], 0, v[176:177]
	v_mul_f32_e32 v94, v94, v94
	v_mul_f32_e32 v91, v91, v91
	v_mul_f32_e32 v92, v92, v92
	v_mul_f32_e32 v93, v93, v93
	v_cvt_pk_bf16_f32 v90, v94, v90
	v_pk_add_f32 v[86:87], v[86:87], v[134:135]
	v_pk_add_f32 v[84:85], v[84:85], v[132:133]
	v_max_f32_e32 v82, 0, v82
	v_cvt_pk_bf16_f32 v91, v91, v92
	v_cvt_pk_bf16_f32 v92, v100, v95
	v_cvt_pk_bf16_f32 v93, v96, v93
	global_store_dwordx4 v[98:99], v[90:93], off
	v_pk_add_f32 v[88:89], v[88:89], v[136:137]
	v_max_f32_e32 v83, 0, v83
	v_mul_f32_e32 v90, v82, v82
	v_max_f32_e32 v82, 0, v87
	v_max_f32_e32 v84, 0, v84
	v_max_f32_e32 v86, 0, v86
	v_mul_f32_e32 v82, v82, v82
	v_mul_f32_e32 v87, v83, v83
	v_max_f32_e32 v83, 0, v88
	v_mul_f32_e32 v88, v84, v84
	v_max_f32_e32 v84, 0, v89
	v_max_f32_e32 v85, 0, v85
	v_mul_f32_e32 v86, v86, v86
	v_mul_f32_e32 v83, v83, v83
	v_mul_f32_e32 v84, v84, v84
	v_mul_f32_e32 v85, v85, v85
	v_cvt_pk_bf16_f32 v82, v86, v82
	v_cvt_pk_bf16_f32 v83, v83, v84
	v_cvt_pk_bf16_f32 v84, v90, v87
	v_cvt_pk_bf16_f32 v85, v88, v85
	global_store_dwordx4 v[98:99], v[82:85], off offset:256
	v_pk_add_f32 v[74:75], v[74:75], v[138:139]
	v_pk_add_f32 v[78:79], v[78:79], v[142:143]
	v_or_b32_e32 v82, 48, v164
	v_ashrrev_i32_e32 v83, 31, v82
	v_pk_add_f32 v[76:77], v[76:77], v[140:141]
	v_max_f32_e32 v74, 0, v74
	v_lshlrev_b64 v[82:83], 13, v[82:83]
	v_pk_add_f32 v[80:81], v[80:81], v[144:145]
	v_mul_f32_e32 v84, v74, v74
	v_max_f32_e32 v74, 0, v79
	v_max_f32_e32 v75, 0, v75
	v_max_f32_e32 v76, 0, v76
	v_lshl_add_u64 v[82:83], s[68:69], 0, v[82:83]
	v_max_f32_e32 v78, 0, v78
	v_mul_f32_e32 v74, v74, v74
	v_mul_f32_e32 v79, v75, v75
	v_max_f32_e32 v75, 0, v80
	v_mul_f32_e32 v80, v76, v76
	v_max_f32_e32 v76, 0, v81
	v_max_f32_e32 v77, 0, v77
	v_pk_add_f32 v[68:69], v[68:69], v[132:133]
	v_pk_add_f32 v[66:67], v[66:67], v[130:131]
	v_lshl_add_u64 v[82:83], v[82:83], 0, v[176:177]
	v_mul_f32_e32 v78, v78, v78
	v_mul_f32_e32 v75, v75, v75
	v_mul_f32_e32 v76, v76, v76
	v_mul_f32_e32 v77, v77, v77
	v_cvt_pk_bf16_f32 v74, v78, v74
	v_pk_add_f32 v[72:73], v[72:73], v[136:137]
	v_pk_add_f32 v[70:71], v[70:71], v[134:135]
	v_max_f32_e32 v66, 0, v66
	v_max_f32_e32 v67, 0, v67
	v_max_f32_e32 v68, 0, v68
	v_cvt_pk_bf16_f32 v75, v75, v76
	v_cvt_pk_bf16_f32 v76, v84, v79
	v_cvt_pk_bf16_f32 v77, v80, v77
	global_store_dwordx4 v[82:83], v[74:77], off
	v_max_f32_e32 v70, 0, v70
	v_max_f32_e32 v69, 0, v69
	v_mul_f32_e32 v74, v66, v66
	v_max_f32_e32 v66, 0, v71
	v_mul_f32_e32 v71, v67, v67
	v_max_f32_e32 v67, 0, v72
	v_mul_f32_e32 v72, v68, v68
	v_max_f32_e32 v68, 0, v73
	v_mul_f32_e32 v66, v66, v66
	v_mul_f32_e32 v67, v67, v67
	v_mul_f32_e32 v68, v68, v68
	v_pk_add_f32 v[58:59], v[58:59], v[138:139]
	v_mul_f32_e32 v70, v70, v70
	v_mul_f32_e32 v69, v69, v69
	v_cvt_pk_bf16_f32 v66, v70, v66
	v_cvt_pk_bf16_f32 v67, v67, v68
	v_cvt_pk_bf16_f32 v68, v74, v71
	v_pk_add_f32 v[62:63], v[62:63], v[142:143]
	v_pk_add_f32 v[60:61], v[60:61], v[140:141]
	v_max_f32_e32 v58, 0, v58
	v_cvt_pk_bf16_f32 v69, v72, v69
	global_store_dwordx4 v[82:83], v[66:69], off offset:256
	v_pk_add_f32 v[64:65], v[64:65], v[144:145]
	v_max_f32_e32 v62, 0, v62
	v_mul_f32_e32 v68, v58, v58
	v_max_f32_e32 v58, 0, v63
	v_max_f32_e32 v59, 0, v59
	v_max_f32_e32 v60, 0, v60
	v_mul_f32_e32 v62, v62, v62
	v_mul_f32_e32 v58, v58, v58
	v_mul_f32_e32 v63, v59, v59
	v_max_f32_e32 v59, 0, v64
	v_mul_f32_e32 v64, v60, v60
	v_max_f32_e32 v60, 0, v65
	v_mul_f32_e32 v59, v59, v59
	v_max_f32_e32 v61, 0, v61
	v_mul_f32_e32 v60, v60, v60
	v_cvt_pk_bf16_f32 v58, v62, v58
	v_add_co_u32_e32 v62, vcc, s73, v162
	v_pk_add_f32 v[52:53], v[52:53], v[132:133]
	v_pk_add_f32 v[50:51], v[50:51], v[130:131]
	v_mul_f32_e32 v61, v61, v61
	v_cvt_pk_bf16_f32 v59, v59, v60
	v_cvt_pk_bf16_f32 v60, v68, v63
	v_addc_co_u32_e32 v63, vcc, 0, v163, vcc
	v_pk_add_f32 v[56:57], v[56:57], v[136:137]
	v_pk_add_f32 v[54:55], v[54:55], v[134:135]
	v_max_f32_e32 v50, 0, v50
	v_max_f32_e32 v51, 0, v51
	v_max_f32_e32 v52, 0, v52
	v_cvt_pk_bf16_f32 v61, v64, v61
	global_store_dwordx4 v[62:63], v[58:61], off
	v_max_f32_e32 v54, 0, v54
	v_max_f32_e32 v53, 0, v53
	v_mul_f32_e32 v58, v50, v50
	v_max_f32_e32 v50, 0, v55
	v_mul_f32_e32 v55, v51, v51
	v_max_f32_e32 v51, 0, v56
	v_mul_f32_e32 v56, v52, v52
	v_max_f32_e32 v52, 0, v57
	v_mul_f32_e32 v50, v50, v50
	v_mul_f32_e32 v51, v51, v51
	v_mul_f32_e32 v52, v52, v52
	v_pk_add_f32 v[42:43], v[42:43], v[138:139]
	v_lshl_add_u64 v[66:67], v[162:163], 0, s[20:21]
	v_mul_f32_e32 v54, v54, v54
	v_mul_f32_e32 v53, v53, v53
	v_cvt_pk_bf16_f32 v50, v54, v50
	v_cvt_pk_bf16_f32 v51, v51, v52
	v_cvt_pk_bf16_f32 v52, v58, v55
	v_pk_add_f32 v[46:47], v[46:47], v[142:143]
	v_pk_add_f32 v[44:45], v[44:45], v[140:141]
	v_max_f32_e32 v42, 0, v42
	v_cvt_pk_bf16_f32 v53, v56, v53
	global_store_dwordx4 v[66:67], v[50:53], off offset:256
	v_pk_add_f32 v[48:49], v[48:49], v[144:145]
	v_max_f32_e32 v46, 0, v46
	v_mul_f32_e32 v52, v42, v42
	v_max_f32_e32 v42, 0, v47
	v_max_f32_e32 v43, 0, v43
	v_max_f32_e32 v44, 0, v44
	v_mul_f32_e32 v46, v46, v46
	v_mul_f32_e32 v42, v42, v42
	v_mul_f32_e32 v47, v43, v43
	v_max_f32_e32 v43, 0, v48
	v_mul_f32_e32 v48, v44, v44
	v_max_f32_e32 v44, 0, v49
	v_mul_f32_e32 v43, v43, v43
	v_max_f32_e32 v45, 0, v45
	v_mul_f32_e32 v44, v44, v44
	v_cvt_pk_bf16_f32 v42, v46, v42
	v_add_co_u32_e32 v46, vcc, s74, v162
	v_pk_add_f32 v[36:37], v[36:37], v[132:133]
	v_pk_add_f32 v[34:35], v[34:35], v[130:131]
	v_mul_f32_e32 v45, v45, v45
	v_cvt_pk_bf16_f32 v43, v43, v44
	v_cvt_pk_bf16_f32 v44, v52, v47
	v_addc_co_u32_e32 v47, vcc, 0, v163, vcc
	v_pk_add_f32 v[40:41], v[40:41], v[136:137]
	v_pk_add_f32 v[38:39], v[38:39], v[134:135]
	v_max_f32_e32 v34, 0, v34
	v_max_f32_e32 v35, 0, v35
	v_max_f32_e32 v36, 0, v36
	v_cvt_pk_bf16_f32 v45, v48, v45
	global_store_dwordx4 v[46:47], v[42:45], off
	v_max_f32_e32 v38, 0, v38
	v_max_f32_e32 v37, 0, v37
	v_mul_f32_e32 v42, v34, v34
	v_max_f32_e32 v34, 0, v39
	v_mul_f32_e32 v39, v35, v35
	v_max_f32_e32 v35, 0, v40
	v_mul_f32_e32 v40, v36, v36
	v_max_f32_e32 v36, 0, v41
	v_mul_f32_e32 v34, v34, v34
	v_mul_f32_e32 v35, v35, v35
	v_mul_f32_e32 v36, v36, v36
	v_pk_add_f32 v[26:27], v[26:27], v[138:139]
	v_lshl_add_u64 v[50:51], v[162:163], 0, s[22:23]
	v_mul_f32_e32 v38, v38, v38
	v_mul_f32_e32 v37, v37, v37
	v_cvt_pk_bf16_f32 v34, v38, v34
	v_cvt_pk_bf16_f32 v35, v35, v36
	v_cvt_pk_bf16_f32 v36, v42, v39
	v_pk_add_f32 v[30:31], v[30:31], v[142:143]
	v_pk_add_f32 v[28:29], v[28:29], v[140:141]
	v_max_f32_e32 v26, 0, v26
	v_cvt_pk_bf16_f32 v37, v40, v37
	global_store_dwordx4 v[50:51], v[34:37], off offset:256
	v_pk_add_f32 v[32:33], v[32:33], v[144:145]
	v_max_f32_e32 v30, 0, v30
	v_mul_f32_e32 v36, v26, v26
	v_max_f32_e32 v26, 0, v31
	v_max_f32_e32 v27, 0, v27
	v_max_f32_e32 v28, 0, v28
	v_mul_f32_e32 v30, v30, v30
	v_mul_f32_e32 v26, v26, v26
	v_mul_f32_e32 v31, v27, v27
	v_max_f32_e32 v27, 0, v32
	v_mul_f32_e32 v32, v28, v28
	v_max_f32_e32 v28, 0, v33
	v_mul_f32_e32 v27, v27, v27
	v_max_f32_e32 v29, 0, v29
	v_mul_f32_e32 v28, v28, v28
	v_cvt_pk_bf16_f32 v26, v30, v26
	v_add_co_u32_e32 v30, vcc, s75, v162
	v_pk_add_f32 v[20:21], v[20:21], v[132:133]
	v_pk_add_f32 v[18:19], v[18:19], v[130:131]
	v_mul_f32_e32 v29, v29, v29
	v_cvt_pk_bf16_f32 v27, v27, v28
	v_cvt_pk_bf16_f32 v28, v36, v31
	v_addc_co_u32_e32 v31, vcc, 0, v163, vcc
	v_pk_add_f32 v[24:25], v[24:25], v[136:137]
	v_pk_add_f32 v[22:23], v[22:23], v[134:135]
	v_max_f32_e32 v18, 0, v18
	v_max_f32_e32 v19, 0, v19
	v_max_f32_e32 v20, 0, v20
	v_cvt_pk_bf16_f32 v29, v32, v29
	global_store_dwordx4 v[30:31], v[26:29], off
	v_max_f32_e32 v22, 0, v22
	v_max_f32_e32 v21, 0, v21
	v_mul_f32_e32 v26, v18, v18
	v_max_f32_e32 v18, 0, v23
	v_mul_f32_e32 v23, v19, v19
	v_max_f32_e32 v19, 0, v24
	v_mul_f32_e32 v24, v20, v20
	v_max_f32_e32 v20, 0, v25
	v_mul_f32_e32 v18, v18, v18
	v_mul_f32_e32 v19, v19, v19
	v_mul_f32_e32 v20, v20, v20
	v_pk_add_f32 v[10:11], v[10:11], v[138:139]
	v_lshl_add_u64 v[34:35], v[162:163], 0, s[24:25]
	v_mul_f32_e32 v22, v22, v22
	v_mul_f32_e32 v21, v21, v21
	v_cvt_pk_bf16_f32 v18, v22, v18
	v_cvt_pk_bf16_f32 v19, v19, v20
	v_cvt_pk_bf16_f32 v20, v26, v23
	v_pk_add_f32 v[14:15], v[14:15], v[142:143]
	v_pk_add_f32 v[12:13], v[12:13], v[140:141]
	v_max_f32_e32 v10, 0, v10
	v_cvt_pk_bf16_f32 v21, v24, v21
	global_store_dwordx4 v[34:35], v[18:21], off offset:256
	v_pk_add_f32 v[16:17], v[16:17], v[144:145]
	v_max_f32_e32 v14, 0, v14
	v_mul_f32_e32 v20, v10, v10
	v_max_f32_e32 v10, 0, v15
	v_max_f32_e32 v11, 0, v11
	v_max_f32_e32 v12, 0, v12
	v_mul_f32_e32 v14, v14, v14
	v_mul_f32_e32 v10, v10, v10
	v_mul_f32_e32 v15, v11, v11
	v_max_f32_e32 v11, 0, v16
	v_mul_f32_e32 v16, v12, v12
	v_max_f32_e32 v12, 0, v17
	v_mul_f32_e32 v11, v11, v11
	v_max_f32_e32 v13, 0, v13
	v_mul_f32_e32 v12, v12, v12
	v_cvt_pk_bf16_f32 v10, v14, v10
	v_add_co_u32_e32 v14, vcc, s76, v162
	v_pk_add_f32 v[4:5], v[4:5], v[132:133]
	v_pk_add_f32 v[2:3], v[2:3], v[130:131]
	v_mul_f32_e32 v13, v13, v13
	v_cvt_pk_bf16_f32 v11, v11, v12
	v_cvt_pk_bf16_f32 v12, v20, v15
	v_addc_co_u32_e32 v15, vcc, 0, v163, vcc
	v_pk_add_f32 v[8:9], v[8:9], v[136:137]
	v_pk_add_f32 v[6:7], v[6:7], v[134:135]
	v_max_f32_e32 v2, 0, v2
	v_max_f32_e32 v3, 0, v3
	v_max_f32_e32 v4, 0, v4
	v_cvt_pk_bf16_f32 v13, v16, v13
	global_store_dwordx4 v[14:15], v[10:13], off
	v_max_f32_e32 v5, 0, v5
	v_lshl_add_u64 v[18:19], v[162:163], 0, s[26:27]
	v_mul_f32_e32 v10, v2, v2
	v_max_f32_e32 v2, 0, v7
	v_mul_f32_e32 v7, v3, v3
	v_max_f32_e32 v3, 0, v8
	v_mul_f32_e32 v8, v4, v4
	v_max_f32_e32 v4, 0, v9
	v_max_f32_e32 v6, 0, v6
	v_mul_f32_e32 v2, v2, v2
	v_mul_f32_e32 v3, v3, v3
	v_mul_f32_e32 v4, v4, v4
	v_mul_f32_e32 v5, v5, v5
	s_andn2_b64 vcc, exec, s[6:7]
	v_mul_f32_e32 v6, v6, v6
	v_cvt_pk_bf16_f32 v2, v6, v2
	v_cvt_pk_bf16_f32 v3, v3, v4
	v_cvt_pk_bf16_f32 v4, v10, v7
	v_cvt_pk_bf16_f32 v5, v8, v5
	global_store_dwordx4 v[18:19], v[2:5], off offset:256
	s_cbranch_vccnz .LBB0_577
	s_andn2_b64 vcc, exec, s[14:15]
	s_cbranch_vccnz .LBB0_576
	s_barrier
	s_branch .LBB0_576
